# code placement phase test: GEMM K-loop heads at a 64-byte boundary plus 32 bytes
# baseline (speedup 1.0000x reference)
.Lgprio0:
	v_add_u32_e32 v236, 0x10000, v175
	v_add_u32_e32 v237, 0x14000, v175
	v_add_u32_e32 v238, 0x18000, v175
	v_add_u32_e32 v239, 0x1c000, v175
	.p2alignl 6, 3212836864
	s_nop 0
	s_nop 0
	s_nop 0
	s_nop 0
	s_nop 0
	s_nop 0
	s_nop 0
	s_nop 0

.Lgprio1:
	v_add_u32_e32 v236, 0x10000, v172
	v_add_u32_e32 v237, 0x14000, v172
	v_add_u32_e32 v238, 0x18000, v172
	v_add_u32_e32 v239, 0x1c000, v172
	.p2alignl 6, 3212836864
	s_nop 0
	s_nop 0
	s_nop 0
	s_nop 0
	s_nop 0
	s_nop 0
	s_nop 0
	s_nop 0

.Lgprio3:
	v_add_u32_e32 v236, 0x10000, v176
	v_add_u32_e32 v237, 0x14000, v176
	v_add_u32_e32 v238, 0x18000, v176
	v_add_u32_e32 v239, 0x1c000, v176
	.p2alignl 6, 3212836864
	s_nop 0
	s_nop 0
	s_nop 0
	s_nop 0
	s_nop 0
	s_nop 0
	s_nop 0
	s_nop 0
